# v36 plus accumulator clear with 64-bit moves
# speedup vs baseline: 1.0115x; 1.0054x over previous
; template <class Epi, class Sched, bool ALIGN_EPI = false, bool SP2 = false>
; __device__ __forceinline__ void gemm_phase(PG8_LAS unsigned char* lds, int tid_in, const Gemm g, const Sched& S, const Epi& E) {
;     ...
;         const bool has_next = S.next(ui + 1, nxt);
;         const char* nA = has_next ? (const char*)g.A + (size_t)nxt.pm * tstep : cA; const char* nB = has_next ? (const char*)g.Bt + (size_t)nxt.pn * tstep : cB;
;         for (int t = 0; t < nt; t += 2) {
;             const bool last = (t == nt - 2);
;             const char* a1 = cA + (size_t)(t + 1) * kstep;
;             const char* a2 = last ? nA : cA + (size_t)(t + 2) * kstep; const char* b2 = last ? nB : cB + (size_t)(t + 2) * kstep;
;             const char* a3 = a2 + kstep; const char* b3 = b2 + kstep;
;     ...
;         for (int a = 0; a < 2; ++a)
; #pragma unroll
;             for (int b = 0; b < 2; ++b)
; #pragma unroll
;                 for (int m = 0; m < 4; ++m)
; #pragma unroll
;                     for (int n = 0; n < 2; ++n) acc[a][b][m][n] = (f32x4){0.f, 0.f, 0.f, 0.f};
.LBB0_136:
	s_ashr_i32 s15, s14, 31
	s_lshl_b64 s[16:17], s[14:15], 19
	v_readlane_b32 s20, v253, 52
	v_readlane_b32 s21, v253, 53
	s_add_u32 s16, s20, s16
	s_addc_u32 s17, s21, s17
	s_and_b64 s[20:21], s[4:5], exec
	s_cselect_b32 s1, s17, s35
	s_cselect_b32 s15, s16, s34
	s_ashr_i32 s13, s12, 31
	s_lshl_b64 s[20:21], s[12:13], 19
	v_readlane_b32 s13, v254, 35
	s_add_u32 s30, s13, s20
	v_readlane_b32 s13, v254, 36
	s_addc_u32 s31, s13, s21
	s_and_b64 s[20:21], s[4:5], exec
	s_cselect_b32 s13, s31, s43
	s_cselect_b32 s20, s30, s42
	s_add_u32 s34, s34, 0x40080
	s_addc_u32 s35, s35, 0
	s_add_u32 s21, s42, 0x100
	v_mov_b32_e32 v0, 0
	s_addc_u32 s28, s43, 0
	s_mov_b32 s29, -2
	v_mov_b32_e32 v1, v0
	v_mov_b32_e32 v2, v0
	v_mov_b32_e32 v3, v0
	v_mov_b32_e32 v4, v0
	v_mov_b32_e32 v5, v0
	v_mov_b32_e32 v6, v0
	v_mov_b32_e32 v7, v0
	v_mov_b32_e32 v10, v0
	v_mov_b32_e32 v11, v0
	v_mov_b32_e32 v12, v0
	v_mov_b32_e32 v13, v0
	v_mov_b32_e32 v18, v0
	v_mov_b32_e32 v19, v0
	v_mov_b32_e32 v20, v0
	v_mov_b32_e32 v21, v0
	v_mov_b32_e32 v26, v0
	v_mov_b32_e32 v27, v0
	v_mov_b32_e32 v28, v0
	v_mov_b32_e32 v29, v0
	s_waitcnt vmcnt(0)
	v_mov_b64_e32 v[34:35], 0
	v_mov_b64_e32 v[36:37], 0
	v_mov_b64_e32 v[42:43], 0
	v_mov_b64_e32 v[44:45], 0
	v_mov_b64_e32 v[50:51], 0
	v_mov_b64_e32 v[52:53], 0
	v_mov_b64_e32 v[14:15], 0
	v_mov_b64_e32 v[16:17], 0
	v_mov_b64_e32 v[22:23], 0
	v_mov_b64_e32 v[24:25], 0
	v_mov_b64_e32 v[30:31], 0
	v_mov_b64_e32 v[32:33], 0
	v_mov_b64_e32 v[38:39], 0
	v_mov_b64_e32 v[40:41], 0
	v_mov_b64_e32 v[46:47], 0
	v_mov_b64_e32 v[48:49], 0
	v_mov_b64_e32 v[54:55], 0
	v_mov_b64_e32 v[56:57], 0
	v_mov_b64_e32 v[58:59], 0
	v_mov_b64_e32 v[60:61], 0
	v_mov_b64_e32 v[62:63], 0
	v_mov_b64_e32 v[64:65], 0
	v_mov_b64_e32 v[66:67], 0
	v_mov_b64_e32 v[68:69], 0
	v_mov_b64_e32 v[70:71], 0
	v_mov_b64_e32 v[72:73], 0
	v_mov_b64_e32 v[74:75], 0
	v_mov_b64_e32 v[76:77], 0
	v_mov_b64_e32 v[82:83], 0
	v_mov_b64_e32 v[84:85], 0
	v_mov_b64_e32 v[90:91], 0
	v_mov_b64_e32 v[92:93], 0
	v_mov_b64_e32 v[98:99], 0
	v_mov_b64_e32 v[100:101], 0
	v_mov_b64_e32 v[106:107], 0
	v_mov_b64_e32 v[108:109], 0
	v_mov_b64_e32 v[114:115], 0
	v_mov_b64_e32 v[116:117], 0
	v_mov_b64_e32 v[78:79], 0
	v_mov_b64_e32 v[80:81], 0
	v_mov_b64_e32 v[86:87], 0
	v_mov_b64_e32 v[88:89], 0
	v_mov_b64_e32 v[94:95], 0
	v_mov_b64_e32 v[96:97], 0
	v_mov_b64_e32 v[102:103], 0
	v_mov_b64_e32 v[104:105], 0
	v_mov_b64_e32 v[110:111], 0
	v_mov_b64_e32 v[112:113], 0
	v_mov_b64_e32 v[118:119], 0
	v_mov_b64_e32 v[120:121], 0
	v_mov_b64_e32 v[122:123], 0
	v_mov_b64_e32 v[124:125], 0
	v_mov_b64_e32 v[126:127], 0
	v_mov_b64_e32 v[128:129], 0

; template <class Epi, class Sched, bool ALIGN_EPI = false, bool SP2 = false>
; __device__ __forceinline__ void gemm_phase(PG8_LAS unsigned char* lds, int tid_in, const Gemm g, const Sched& S, const Epi& E) {
;     ...
;         const bool has_next = S.next(ui + 1, nxt);
;         const char* nA = has_next ? (const char*)g.A + (size_t)nxt.pm * tstep : cA; const char* nB = has_next ? (const char*)g.Bt + (size_t)nxt.pn * tstep : cB;
;         for (int t = 0; t < nt; t += 2) {
;             const bool last = (t == nt - 2);
;             const char* a1 = cA + (size_t)(t + 1) * kstep;
;             const char* a2 = last ? nA : cA + (size_t)(t + 2) * kstep; const char* b2 = last ? nB : cB + (size_t)(t + 2) * kstep;
;             const char* a3 = a2 + kstep; const char* b3 = b2 + kstep;
;     ...
;         for (int a = 0; a < 2; ++a)
; #pragma unroll
;             for (int b = 0; b < 2; ++b)
; #pragma unroll
;                 for (int m = 0; m < 4; ++m)
; #pragma unroll
;                     for (int n = 0; n < 2; ++n) acc[a][b][m][n] = (f32x4){0.f, 0.f, 0.f, 0.f};
.LBB0_591:
	s_ashr_i32 s15, s14, 31
	s_lshl_b64 s[16:17], s[14:15], 18
	v_readlane_b32 s30, v253, 26
	v_readlane_b32 s31, v253, 27
	s_add_u32 s16, s30, s16
	s_addc_u32 s17, s31, s17
	s_and_b64 s[30:31], s[6:7], exec
	s_cselect_b32 s15, s17, s35
	s_cselect_b32 s53, s16, s34
	s_ashr_i32 s13, s12, 31
	s_lshl_b64 s[30:31], s[12:13], 18
	s_add_u32 s30, s0, s30
	s_addc_u32 s31, s1, s31
	s_and_b64 s[36:37], s[6:7], exec
	s_cselect_b32 s13, s31, s43
	s_cselect_b32 s38, s30, s42
	s_add_u32 s34, s34, 0x20080
	s_addc_u32 s35, s35, 0
	s_add_u32 s39, s42, 0x100
	v_mov_b32_e32 v0, 0
	s_addc_u32 s36, s43, 0
	s_mov_b32 s37, -2
	v_mov_b32_e32 v1, v0
	v_mov_b32_e32 v2, v0
	v_mov_b32_e32 v3, v0
	v_mov_b32_e32 v4, v0
	v_mov_b32_e32 v5, v0
	v_mov_b32_e32 v6, v0
	v_mov_b32_e32 v7, v0
	v_mov_b32_e32 v18, v0
	v_mov_b32_e32 v19, v0
	v_mov_b32_e32 v20, v0
	v_mov_b32_e32 v21, v0
	v_mov_b32_e32 v22, v0
	v_mov_b32_e32 v23, v0
	v_mov_b32_e32 v24, v0
	v_mov_b32_e32 v25, v0
	s_waitcnt vmcnt(0)
	v_mov_b64_e32 v[34:35], 0
	v_mov_b64_e32 v[36:37], 0
	v_mov_b64_e32 v[38:39], 0
	v_mov_b64_e32 v[40:41], 0
	v_mov_b64_e32 v[50:51], 0
	v_mov_b64_e32 v[52:53], 0
	v_mov_b64_e32 v[54:55], 0
	v_mov_b64_e32 v[56:57], 0
	v_mov_b64_e32 v[10:11], 0
	v_mov_b64_e32 v[12:13], 0
	v_mov_b64_e32 v[14:15], 0
	v_mov_b64_e32 v[16:17], 0
	v_mov_b64_e32 v[26:27], 0
	v_mov_b64_e32 v[28:29], 0
	v_mov_b64_e32 v[30:31], 0
	v_mov_b64_e32 v[32:33], 0
	v_mov_b64_e32 v[42:43], 0
	v_mov_b64_e32 v[44:45], 0
	v_mov_b64_e32 v[46:47], 0
	v_mov_b64_e32 v[48:49], 0
	v_mov_b64_e32 v[58:59], 0
	v_mov_b64_e32 v[60:61], 0
	v_mov_b64_e32 v[62:63], 0
	v_mov_b64_e32 v[64:65], 0
	v_mov_b64_e32 v[66:67], 0
	v_mov_b64_e32 v[68:69], 0
	v_mov_b64_e32 v[70:71], 0
	v_mov_b64_e32 v[72:73], 0
	v_mov_b64_e32 v[82:83], 0
	v_mov_b64_e32 v[84:85], 0
	v_mov_b64_e32 v[86:87], 0
	v_mov_b64_e32 v[88:89], 0
	v_mov_b64_e32 v[98:99], 0
	v_mov_b64_e32 v[100:101], 0
	v_mov_b64_e32 v[102:103], 0
	v_mov_b64_e32 v[104:105], 0
	v_mov_b64_e32 v[114:115], 0
	v_mov_b64_e32 v[116:117], 0
	v_mov_b64_e32 v[122:123], 0
	v_mov_b64_e32 v[124:125], 0
	v_mov_b64_e32 v[74:75], 0
	v_mov_b64_e32 v[76:77], 0
	v_mov_b64_e32 v[78:79], 0
	v_mov_b64_e32 v[80:81], 0
	v_mov_b64_e32 v[90:91], 0
	v_mov_b64_e32 v[92:93], 0
	v_mov_b64_e32 v[94:95], 0
	v_mov_b64_e32 v[96:97], 0
	v_mov_b64_e32 v[106:107], 0
	v_mov_b64_e32 v[108:109], 0
	v_mov_b64_e32 v[110:111], 0
	v_mov_b64_e32 v[112:113], 0
	v_mov_b64_e32 v[142:143], 0
	v_mov_b64_e32 v[144:145], 0
	v_mov_b64_e32 v[146:147], 0
	v_mov_b64_e32 v[148:149], 0

; template <class Epi, class Sched, bool ALIGN_EPI = false, bool SP2 = false>
; __device__ __forceinline__ void gemm_phase(PG8_LAS unsigned char* lds, int tid_in, const Gemm g, const Sched& S, const Epi& E) {
;     ...
;         const bool has_next = S.next(ui + 1, nxt);
;         const char* nA = has_next ? (const char*)g.A + (size_t)nxt.pm * tstep : cA; const char* nB = has_next ? (const char*)g.Bt + (size_t)nxt.pn * tstep : cB;
;         for (int t = 0; t < nt; t += 2) {
;             const bool last = (t == nt - 2);
;             const char* a1 = cA + (size_t)(t + 1) * kstep;
;             const char* a2 = last ? nA : cA + (size_t)(t + 2) * kstep; const char* b2 = last ? nB : cB + (size_t)(t + 2) * kstep;
;             const char* a3 = a2 + kstep; const char* b3 = b2 + kstep;
;     ...
;         for (int a = 0; a < 2; ++a)
; #pragma unroll
;             for (int b = 0; b < 2; ++b)
; #pragma unroll
;                 for (int m = 0; m < 4; ++m)
; #pragma unroll
;                     for (int n = 0; n < 2; ++n) acc[a][b][m][n] = (f32x4){0.f, 0.f, 0.f, 0.f};
.LBB0_707:
	s_ashr_i32 s17, s16, 31
	s_lshl_b64 s[30:31], s[16:17], 19
	s_add_u32 s30, s46, s30
	s_addc_u32 s31, s47, s31
	s_and_b64 s[34:35], s[4:5], exec
	s_cselect_b32 s17, s31, s49
	s_cselect_b32 s96, s30, s48
	s_ashr_i32 s15, s14, 31
	s_lshl_b64 s[34:35], s[14:15], 19
	s_add_u32 s34, s33, s34
	s_addc_u32 s35, s60, s35
	s_and_b64 s[36:37], s[4:5], exec
	s_cselect_b32 s15, s35, s51
	s_cselect_b32 s38, s34, s50
	s_add_u32 s48, s48, 0x40080
	s_addc_u32 s49, s49, 0
	s_add_u32 s39, s50, 0x100
	v_mov_b32_e32 v0, 0
	s_addc_u32 s36, s51, 0
	s_mov_b32 s37, -2
	v_mov_b32_e32 v1, v0
	v_mov_b32_e32 v2, v0
	v_mov_b32_e32 v3, v0
	v_mov_b32_e32 v4, v0
	v_mov_b32_e32 v5, v0
	v_mov_b32_e32 v6, v0
	v_mov_b32_e32 v7, v0
	v_mov_b32_e32 v18, v0
	v_mov_b32_e32 v19, v0
	v_mov_b32_e32 v20, v0
	v_mov_b32_e32 v21, v0
	v_mov_b32_e32 v22, v0
	v_mov_b32_e32 v23, v0
	v_mov_b32_e32 v24, v0
	v_mov_b32_e32 v25, v0
	s_waitcnt vmcnt(0)
	v_mov_b64_e32 v[34:35], 0
	v_mov_b64_e32 v[36:37], 0
	v_mov_b64_e32 v[38:39], 0
	v_mov_b64_e32 v[40:41], 0
	v_mov_b64_e32 v[50:51], 0
	v_mov_b64_e32 v[52:53], 0
	v_mov_b64_e32 v[54:55], 0
	v_mov_b64_e32 v[56:57], 0
	v_mov_b64_e32 v[10:11], 0
	v_mov_b64_e32 v[12:13], 0
	v_mov_b64_e32 v[14:15], 0
	v_mov_b64_e32 v[16:17], 0
	v_mov_b64_e32 v[26:27], 0
	v_mov_b64_e32 v[28:29], 0
	v_mov_b64_e32 v[30:31], 0
	v_mov_b64_e32 v[32:33], 0
	v_mov_b64_e32 v[42:43], 0
	v_mov_b64_e32 v[44:45], 0
	v_mov_b64_e32 v[46:47], 0
	v_mov_b64_e32 v[48:49], 0
	v_mov_b64_e32 v[58:59], 0
	v_mov_b64_e32 v[60:61], 0
	v_mov_b64_e32 v[62:63], 0
	v_mov_b64_e32 v[64:65], 0
	v_mov_b64_e32 v[66:67], 0
	v_mov_b64_e32 v[68:69], 0
	v_mov_b64_e32 v[70:71], 0
	v_mov_b64_e32 v[72:73], 0
	v_mov_b64_e32 v[82:83], 0
	v_mov_b64_e32 v[84:85], 0
	v_mov_b64_e32 v[86:87], 0
	v_mov_b64_e32 v[88:89], 0
	v_mov_b64_e32 v[98:99], 0
	v_mov_b64_e32 v[100:101], 0
	v_mov_b64_e32 v[102:103], 0
	v_mov_b64_e32 v[104:105], 0
	v_mov_b64_e32 v[114:115], 0
	v_mov_b64_e32 v[116:117], 0
	v_mov_b64_e32 v[118:119], 0
	v_mov_b64_e32 v[120:121], 0
	v_mov_b64_e32 v[74:75], 0
	v_mov_b64_e32 v[76:77], 0
	v_mov_b64_e32 v[78:79], 0
	v_mov_b64_e32 v[80:81], 0
	v_mov_b64_e32 v[90:91], 0
	v_mov_b64_e32 v[92:93], 0
	v_mov_b64_e32 v[94:95], 0
	v_mov_b64_e32 v[96:97], 0
	v_mov_b64_e32 v[106:107], 0
	v_mov_b64_e32 v[108:109], 0
	v_mov_b64_e32 v[110:111], 0
	v_mov_b64_e32 v[112:113], 0
	v_mov_b64_e32 v[138:139], 0
	v_mov_b64_e32 v[140:141], 0
	v_mov_b64_e32 v[142:143], 0
	v_mov_b64_e32 v[144:145], 0

; template <class Epi, class Sched, bool ALIGN_EPI = false, bool SP2 = false>
; __device__ __forceinline__ void gemm_phase(PG8_LAS unsigned char* lds, int tid_in, const Gemm g, const Sched& S, const Epi& E) {
;     ...
;         const bool has_next = S.next(ui + 1, nxt);
;         const char* nA = has_next ? (const char*)g.A + (size_t)nxt.pm * tstep : cA; const char* nB = has_next ? (const char*)g.Bt + (size_t)nxt.pn * tstep : cB;
;         for (int t = 0; t < nt; t += 2) {
;             const bool last = (t == nt - 2);
;             const char* a1 = cA + (size_t)(t + 1) * kstep;
;             const char* a2 = last ? nA : cA + (size_t)(t + 2) * kstep; const char* b2 = last ? nB : cB + (size_t)(t + 2) * kstep;
;             const char* a3 = a2 + kstep; const char* b3 = b2 + kstep;
;     ...
;         for (int a = 0; a < 2; ++a)
; #pragma unroll
;             for (int b = 0; b < 2; ++b)
; #pragma unroll
;                 for (int m = 0; m < 4; ++m)
; #pragma unroll
;                     for (int n = 0; n < 2; ++n) acc[a][b][m][n] = (f32x4){0.f, 0.f, 0.f, 0.f};
.LBB0_834:
	s_ashr_i32 s17, s16, 31
	s_lshl_b64 s[8:9], s[16:17], 19
	v_readlane_b32 s30, v253, 52
	v_readlane_b32 s31, v253, 53
	s_add_u32 s8, s30, s8
	s_addc_u32 s9, s31, s9
	s_and_b64 s[30:31], s[4:5], exec
	s_cselect_b32 s17, s9, s35
	s_cselect_b32 s53, s8, s34
	s_ashr_i32 s15, s14, 31
	s_lshl_b64 s[30:31], s[14:15], 19
	s_add_u32 s30, s33, s30
	s_addc_u32 s31, s40, s31
	s_and_b64 s[36:37], s[4:5], exec
	s_cselect_b32 s15, s31, s43
	s_cselect_b32 s38, s30, s42
	s_add_u32 s34, s34, 0x40080
	s_addc_u32 s35, s35, 0
	s_add_u32 s39, s42, 0x100
	v_mov_b32_e32 v0, 0
	s_addc_u32 s36, s43, 0
	s_mov_b32 s37, -2
	v_mov_b32_e32 v1, v0
	v_mov_b32_e32 v2, v0
	v_mov_b32_e32 v3, v0
	v_mov_b32_e32 v4, v0
	v_mov_b32_e32 v5, v0
	v_mov_b32_e32 v6, v0
	v_mov_b32_e32 v7, v0
	v_mov_b32_e32 v18, v0
	v_mov_b32_e32 v19, v0
	v_mov_b32_e32 v20, v0
	v_mov_b32_e32 v21, v0
	v_mov_b32_e32 v22, v0
	v_mov_b32_e32 v23, v0
	v_mov_b32_e32 v24, v0
	v_mov_b32_e32 v25, v0
	s_waitcnt vmcnt(0)
	v_mov_b64_e32 v[34:35], 0
	v_mov_b64_e32 v[36:37], 0
	v_mov_b64_e32 v[38:39], 0
	v_mov_b64_e32 v[40:41], 0
	v_mov_b64_e32 v[50:51], 0
	v_mov_b64_e32 v[52:53], 0
	v_mov_b64_e32 v[54:55], 0
	v_mov_b64_e32 v[56:57], 0
	v_mov_b64_e32 v[10:11], 0
	v_mov_b64_e32 v[12:13], 0
	v_mov_b64_e32 v[14:15], 0
	v_mov_b64_e32 v[16:17], 0
	v_mov_b64_e32 v[26:27], 0
	v_mov_b64_e32 v[28:29], 0
	v_mov_b64_e32 v[30:31], 0
	v_mov_b64_e32 v[32:33], 0
	v_mov_b64_e32 v[42:43], 0
	v_mov_b64_e32 v[44:45], 0
	v_mov_b64_e32 v[46:47], 0
	v_mov_b64_e32 v[48:49], 0
	v_mov_b64_e32 v[58:59], 0
	v_mov_b64_e32 v[60:61], 0
	v_mov_b64_e32 v[62:63], 0
	v_mov_b64_e32 v[64:65], 0
	v_mov_b64_e32 v[66:67], 0
	v_mov_b64_e32 v[68:69], 0
	v_mov_b64_e32 v[70:71], 0
	v_mov_b64_e32 v[72:73], 0
	v_mov_b64_e32 v[82:83], 0
	v_mov_b64_e32 v[84:85], 0
	v_mov_b64_e32 v[86:87], 0
	v_mov_b64_e32 v[88:89], 0
	v_mov_b64_e32 v[98:99], 0
	v_mov_b64_e32 v[100:101], 0
	v_mov_b64_e32 v[102:103], 0
	v_mov_b64_e32 v[104:105], 0
	v_mov_b64_e32 v[130:131], 0
	v_mov_b64_e32 v[132:133], 0
	v_mov_b64_e32 v[134:135], 0
	v_mov_b64_e32 v[136:137], 0
	v_mov_b64_e32 v[74:75], 0
	v_mov_b64_e32 v[76:77], 0
	v_mov_b64_e32 v[78:79], 0
	v_mov_b64_e32 v[80:81], 0
	v_mov_b64_e32 v[90:91], 0
	v_mov_b64_e32 v[92:93], 0
	v_mov_b64_e32 v[94:95], 0
	v_mov_b64_e32 v[96:97], 0
	v_mov_b64_e32 v[122:123], 0
	v_mov_b64_e32 v[124:125], 0
	v_mov_b64_e32 v[126:127], 0
	v_mov_b64_e32 v[128:129], 0
	v_mov_b64_e32 v[138:139], 0
	v_mov_b64_e32 v[140:141], 0
	v_mov_b64_e32 v[142:143], 0
	v_mov_b64_e32 v[144:145], 0

; template <class Epi, class Sched, bool ALIGN_EPI = false, bool SP2 = false>
; __device__ __forceinline__ void gemm_phase(PG8_LAS unsigned char* lds, int tid_in, const Gemm g, const Sched& S, const Epi& E) {
;     ...
;         const bool has_next = S.next(ui + 1, nxt);
;         const char* nA = has_next ? (const char*)g.A + (size_t)nxt.pm * tstep : cA; const char* nB = has_next ? (const char*)g.Bt + (size_t)nxt.pn * tstep : cB;
;         for (int t = 0; t < nt; t += 2) {
;             const bool last = (t == nt - 2);
;             const char* a1 = cA + (size_t)(t + 1) * kstep;
;             const char* a2 = last ? nA : cA + (size_t)(t + 2) * kstep; const char* b2 = last ? nB : cB + (size_t)(t + 2) * kstep;
;             const char* a3 = a2 + kstep; const char* b3 = b2 + kstep;
;     ...
;         for (int a = 0; a < 2; ++a)
; #pragma unroll
;             for (int b = 0; b < 2; ++b)
; #pragma unroll
;                 for (int m = 0; m < 4; ++m)
; #pragma unroll
;                     for (int n = 0; n < 2; ++n) acc[a][b][m][n] = (f32x4){0.f, 0.f, 0.f, 0.f};
.LBB0_914:
	s_ashr_i32 s59, s58, 31
	s_lshl_b64 s[36:37], s[58:59], 21
	s_add_u32 s50, s47, s36
	s_addc_u32 s51, s97, s37
	s_and_b64 s[36:37], s[4:5], exec
	s_cselect_b32 s59, s51, s7
	s_cselect_b32 s38, s50, s6
	s_ashr_i32 s43, s42, 31
	s_lshl_b64 s[36:37], s[42:43], 21
	s_add_u32 s60, s57, s36
	s_addc_u32 s61, s33, s37
	s_and_b64 s[36:37], s[4:5], exec
	s_cselect_b32 s39, s61, s9
	s_cselect_b32 s43, s60, s8
	s_add_u32 s6, s6, 0x100080
	s_addc_u32 s7, s7, 0
	s_add_u32 s36, s8, 0x100
	v_mov_b32_e32 v0, 0
	s_addc_u32 s37, s9, 0
	s_mov_b32 s18, -2
	v_mov_b32_e32 v1, v0
	v_mov_b32_e32 v2, v0
	v_mov_b32_e32 v3, v0
	v_mov_b32_e32 v4, v0
	v_mov_b32_e32 v5, v0
	v_mov_b32_e32 v6, v0
	v_mov_b32_e32 v7, v0
	v_mov_b32_e32 v18, v0
	v_mov_b32_e32 v19, v0
	v_mov_b32_e32 v20, v0
	v_mov_b32_e32 v21, v0
	v_mov_b32_e32 v22, v0
	v_mov_b32_e32 v23, v0
	v_mov_b32_e32 v24, v0
	v_mov_b32_e32 v25, v0
	s_waitcnt vmcnt(0)
	v_mov_b64_e32 v[34:35], 0
	v_mov_b64_e32 v[36:37], 0
	v_mov_b64_e32 v[38:39], 0
	v_mov_b64_e32 v[40:41], 0
	v_mov_b64_e32 v[50:51], 0
	v_mov_b64_e32 v[52:53], 0
	v_mov_b64_e32 v[54:55], 0
	v_mov_b64_e32 v[56:57], 0
	v_mov_b64_e32 v[10:11], 0
	v_mov_b64_e32 v[12:13], 0
	v_mov_b64_e32 v[14:15], 0
	v_mov_b64_e32 v[16:17], 0
	v_mov_b64_e32 v[26:27], 0
	v_mov_b64_e32 v[28:29], 0
	v_mov_b64_e32 v[30:31], 0
	v_mov_b64_e32 v[32:33], 0
	v_mov_b64_e32 v[42:43], 0
	v_mov_b64_e32 v[44:45], 0
	v_mov_b64_e32 v[46:47], 0
	v_mov_b64_e32 v[48:49], 0
	v_mov_b64_e32 v[58:59], 0
	v_mov_b64_e32 v[60:61], 0
	v_mov_b64_e32 v[62:63], 0
	v_mov_b64_e32 v[64:65], 0
	v_mov_b64_e32 v[66:67], 0
	v_mov_b64_e32 v[68:69], 0
	v_mov_b64_e32 v[70:71], 0
	v_mov_b64_e32 v[72:73], 0
	v_mov_b64_e32 v[82:83], 0
	v_mov_b64_e32 v[84:85], 0
	v_mov_b64_e32 v[86:87], 0
	v_mov_b64_e32 v[88:89], 0
	v_mov_b64_e32 v[98:99], 0
	v_mov_b64_e32 v[100:101], 0
	v_mov_b64_e32 v[102:103], 0
	v_mov_b64_e32 v[104:105], 0
	v_mov_b64_e32 v[130:131], 0
	v_mov_b64_e32 v[132:133], 0
	v_mov_b64_e32 v[138:139], 0
	v_mov_b64_e32 v[140:141], 0
	v_mov_b64_e32 v[74:75], 0
	v_mov_b64_e32 v[76:77], 0
	v_mov_b64_e32 v[78:79], 0
	v_mov_b64_e32 v[80:81], 0
	v_mov_b64_e32 v[90:91], 0
	v_mov_b64_e32 v[92:93], 0
	v_mov_b64_e32 v[94:95], 0
	v_mov_b64_e32 v[96:97], 0
	v_mov_b64_e32 v[106:107], 0
	v_mov_b64_e32 v[108:109], 0
	v_mov_b64_e32 v[114:115], 0
	v_mov_b64_e32 v[116:117], 0
	v_mov_b64_e32 v[158:159], 0
	v_mov_b64_e32 v[160:161], 0
	v_mov_b64_e32 v[162:163], 0
	v_mov_b64_e32 v[164:165], 0
